# softmax epilogue: xor-16/xor-32 max and sum reductions use v_permlane16/32_swap instead of ds_bpermute
# baseline (speedup 1.0000x reference)
.LBB7_1222:
	v_and_b32_e32 v19, 64, v163
	v_xor_b32_e32 v18, 16, v163
	v_add_u32_e32 v19, 64, v19
	v_cmp_lt_i32_e32 vcc, v18, v19
	v_max_f32_e32 v20, v128, v128
	v_max_f32_e32 v21, v126, v126
	v_cndmask_b32_e32 v18, v163, v18, vcc
	v_lshlrev_b32_e32 v183, 2, v18
	v_max_f32_e32 v18, v129, v129
	v_max_f32_e32 v18, v20, v18
	v_max_f32_e32 v20, v127, v127
	v_max_f32_e32 v20, v21, v20
	v_max3_f32 v18, v144, v145, v18
	v_max3_f32 v20, v140, v141, v20
	v_max3_f32 v18, v18, s76, v20
	v_max_f32_e32 v20, v147, v147
	v_max_f32_e32 v21, v146, v146
	v_max_f32_e32 v20, v21, v20
	v_max_f32_e32 v21, v143, v143
	v_max_f32_e32 v26, v142, v142
	v_max_f32_e32 v21, v26, v21
	v_max3_f32 v20, v150, v151, v20
	v_max3_f32 v21, v148, v149, v21
	v_max3_f32 v18, v18, v20, v21
	ds_bpermute_b32 v20, v183, v18
	v_xor_b32_e32 v21, 32, v163
	v_cmp_lt_i32_e32 vcc, v21, v19
	s_nop 1
	v_cndmask_b32_e32 v19, v163, v21, vcc
	v_lshlrev_b32_e32 v184, 2, v19
	s_waitcnt lgkmcnt(0)
	v_max_f32_e32 v19, v20, v20
	v_max_f32_e32 v18, v18, v19
	v_mov_b32_e32 v19, v18
	s_nop 1
	v_permlane32_swap_b32_e32 v18, v19
	s_and_saveexec_b64 s[16:17], s[40:41]
	s_cbranch_execz .LBB7_1224
	s_waitcnt lgkmcnt(0)
	v_max_f32_e32 v19, v19, v19
	v_max_f32_e32 v18, v18, v18
	v_max_f32_e32 v18, v18, v19
	v_add_u32_e32 v19, s73, v159
	ds_write_b32 v19, v18
.LBB7_1224:
	s_or_b64 exec, exec, s[16:17]
	v_max_f32_e32 v18, v121, v121
	s_waitcnt lgkmcnt(0)
	v_max_f32_e32 v19, v120, v120
	v_max_f32_e32 v18, v19, v18
	v_max_f32_e32 v19, v111, v111
	v_max_f32_e32 v20, v110, v110
	v_max_f32_e32 v19, v20, v19
	v_max3_f32 v18, v118, v119, v18
	v_max3_f32 v19, v112, v113, v19
	v_max3_f32 v18, v18, s76, v19
	v_max_f32_e32 v19, v117, v117
	v_max_f32_e32 v20, v116, v116
	v_max_f32_e32 v19, v20, v19
	v_max_f32_e32 v20, v115, v115
	v_max_f32_e32 v21, v114, v114
	v_max_f32_e32 v20, v21, v20
	v_max3_f32 v19, v124, v125, v19
	v_max3_f32 v20, v122, v123, v20
	v_max3_f32 v18, v18, v19, v20
	v_mov_b32_e32 v19, v18
	s_nop 1
	v_permlane16_swap_b32_e32 v18, v19
	s_waitcnt lgkmcnt(0)
	v_max_f32_e32 v19, v19, v19
	v_max_f32_e32 v18, v18, v19
	v_mov_b32_e32 v19, v18
	s_nop 1
	v_permlane32_swap_b32_e32 v18, v19
	s_and_saveexec_b64 s[16:17], s[40:41]
	s_cbranch_execz .LBB7_1226
	s_waitcnt lgkmcnt(0)
	v_max_f32_e32 v19, v19, v19
	v_max_f32_e32 v18, v18, v18
	v_max_f32_e32 v18, v18, v19
	v_add_u32_e32 v19, s73, v159
	ds_write_b32 v19, v18 offset:256
.LBB7_1226:
	s_or_b64 exec, exec, s[16:17]
	v_max_f32_e32 v18, v103, v103
	s_waitcnt lgkmcnt(0)
	v_max_f32_e32 v19, v102, v102
	v_max_f32_e32 v18, v19, v18
	v_max_f32_e32 v19, v95, v95
	v_max_f32_e32 v20, v94, v94
	v_max_f32_e32 v19, v20, v19
	v_max3_f32 v18, v104, v105, v18
	v_max3_f32 v19, v96, v97, v19
	v_max3_f32 v18, v18, s76, v19
	v_max_f32_e32 v19, v101, v101
	v_max_f32_e32 v20, v100, v100
	v_max_f32_e32 v19, v20, v19
	v_max_f32_e32 v20, v99, v99
	v_max_f32_e32 v21, v98, v98
	v_max_f32_e32 v20, v21, v20
	v_max3_f32 v19, v108, v109, v19
	v_max3_f32 v20, v106, v107, v20
	v_max3_f32 v18, v18, v19, v20
	v_mov_b32_e32 v19, v18
	s_nop 1
	v_permlane16_swap_b32_e32 v18, v19
	s_waitcnt lgkmcnt(0)
	v_max_f32_e32 v19, v19, v19
	v_max_f32_e32 v18, v18, v19
	v_mov_b32_e32 v19, v18
	s_nop 1
	v_permlane32_swap_b32_e32 v18, v19
	s_and_saveexec_b64 s[16:17], s[40:41]
	s_cbranch_execz .LBB7_1228
	s_waitcnt lgkmcnt(0)
	v_max_f32_e32 v19, v19, v19
	v_max_f32_e32 v18, v18, v18
	v_max_f32_e32 v18, v18, v19
	v_add_u32_e32 v19, s73, v159
	ds_write_b32 v19, v18 offset:512
.LBB7_1228:
	s_or_b64 exec, exec, s[16:17]
	v_max_f32_e32 v18, v87, v87
	s_waitcnt lgkmcnt(0)
	v_max_f32_e32 v19, v86, v86
	v_max_f32_e32 v18, v19, v18
	v_max_f32_e32 v19, v77, v77
	v_max_f32_e32 v20, v76, v76
	v_max_f32_e32 v19, v20, v19
	v_max3_f32 v18, v88, v89, v18
	v_max3_f32 v19, v80, v81, v19
	v_max3_f32 v18, v18, s76, v19
	v_max_f32_e32 v19, v85, v85
	v_max_f32_e32 v20, v84, v84
	v_max_f32_e32 v19, v20, v19
	v_max_f32_e32 v20, v83, v83
	v_max_f32_e32 v21, v82, v82
	v_max_f32_e32 v20, v21, v20
	v_max3_f32 v19, v92, v93, v19
	v_max3_f32 v20, v90, v91, v20
	v_max3_f32 v18, v18, v19, v20
	v_mov_b32_e32 v19, v18
	s_nop 1
	v_permlane16_swap_b32_e32 v18, v19
	s_waitcnt lgkmcnt(0)
	v_max_f32_e32 v19, v19, v19
	v_max_f32_e32 v18, v18, v19
	v_mov_b32_e32 v19, v18
	s_nop 1
	v_permlane32_swap_b32_e32 v18, v19
	s_and_saveexec_b64 s[16:17], s[40:41]
	s_cbranch_execz .LBB7_1230
	s_waitcnt lgkmcnt(0)
	v_max_f32_e32 v19, v19, v19
	v_max_f32_e32 v18, v18, v18
	v_max_f32_e32 v18, v18, v19
	v_add_u32_e32 v19, s73, v159
	ds_write_b32 v19, v18 offset:768
.LBB7_1230:
	s_or_b64 exec, exec, s[16:17]
	v_max_f32_e32 v18, v67, v67
	s_waitcnt lgkmcnt(0)
	v_max_f32_e32 v19, v66, v66
	v_max_f32_e32 v18, v19, v18
	v_max_f32_e32 v19, v63, v63
	v_max_f32_e32 v20, v62, v62
	v_max_f32_e32 v19, v20, v19
	v_max3_f32 v18, v72, v73, v18
	v_max3_f32 v19, v64, v65, v19
	v_max3_f32 v18, v18, s76, v19
	v_max_f32_e32 v19, v71, v71
	v_max_f32_e32 v20, v70, v70
	v_max_f32_e32 v19, v20, v19
	v_max_f32_e32 v20, v69, v69
	v_max_f32_e32 v21, v68, v68
	v_max_f32_e32 v20, v21, v20
	v_max3_f32 v19, v78, v79, v19
	v_max3_f32 v20, v74, v75, v20
	v_max3_f32 v18, v18, v19, v20
	v_mov_b32_e32 v19, v18
	s_nop 1
	v_permlane16_swap_b32_e32 v18, v19
	s_waitcnt lgkmcnt(0)
	v_max_f32_e32 v19, v19, v19
	v_max_f32_e32 v18, v18, v19
	v_mov_b32_e32 v19, v18
	s_nop 1
	v_permlane32_swap_b32_e32 v18, v19
	s_and_saveexec_b64 s[16:17], s[40:41]
	s_cbranch_execz .LBB7_1232
	s_waitcnt lgkmcnt(0)
	v_max_f32_e32 v19, v19, v19
	v_max_f32_e32 v18, v18, v18
	v_max_f32_e32 v18, v18, v19
	v_add_u32_e32 v19, s73, v159
	ds_write_b32 v19, v18 offset:2048
.LBB7_1232:
	s_or_b64 exec, exec, s[16:17]
	v_max_f32_e32 v18, v57, v57
	s_waitcnt lgkmcnt(0)
	v_max_f32_e32 v19, v56, v56
	v_max_f32_e32 v18, v19, v18
	v_max_f32_e32 v19, v47, v47
	v_max_f32_e32 v20, v46, v46
	v_max_f32_e32 v19, v20, v19
	v_max3_f32 v18, v54, v55, v18
	v_max3_f32 v19, v48, v49, v19
	v_max3_f32 v18, v18, s76, v19
	v_max_f32_e32 v19, v53, v53
	v_max_f32_e32 v20, v52, v52
	v_max_f32_e32 v19, v20, v19
	v_max_f32_e32 v20, v51, v51
	v_max_f32_e32 v21, v50, v50
	v_max_f32_e32 v20, v21, v20
	v_max3_f32 v19, v60, v61, v19
	v_max3_f32 v20, v58, v59, v20
	v_max3_f32 v18, v18, v19, v20
	v_mov_b32_e32 v19, v18
	s_nop 1
	v_permlane16_swap_b32_e32 v18, v19
	s_waitcnt lgkmcnt(0)
	v_max_f32_e32 v19, v19, v19
	v_max_f32_e32 v18, v18, v19
	v_mov_b32_e32 v19, v18
	s_nop 1
	v_permlane32_swap_b32_e32 v18, v19
	s_and_saveexec_b64 s[16:17], s[40:41]
	s_cbranch_execz .LBB7_1234
	s_waitcnt lgkmcnt(0)
	v_max_f32_e32 v19, v19, v19
	v_max_f32_e32 v18, v18, v18
	v_max_f32_e32 v18, v18, v19
	v_add_u32_e32 v19, s73, v159
	ds_write_b32 v19, v18 offset:2304
.LBB7_1234:
	s_or_b64 exec, exec, s[16:17]
	v_max_f32_e32 v18, v31, v31
	s_waitcnt lgkmcnt(0)
	v_max_f32_e32 v19, v30, v30
	v_max_f32_e32 v18, v19, v18
	v_max_f32_e32 v19, v23, v23
	v_max_f32_e32 v20, v22, v22
	v_max_f32_e32 v19, v20, v19
	v_max3_f32 v18, v38, v39, v18
	v_max3_f32 v19, v24, v25, v19
	v_max3_f32 v18, v18, s76, v19
	v_max_f32_e32 v19, v35, v35
	v_max_f32_e32 v20, v34, v34
	v_max_f32_e32 v19, v20, v19
	v_max_f32_e32 v20, v33, v33
	v_max_f32_e32 v21, v32, v32
	v_max_f32_e32 v20, v21, v20
	v_max3_f32 v19, v40, v41, v19
	v_max3_f32 v20, v36, v37, v20
	v_max3_f32 v18, v18, v19, v20
	v_mov_b32_e32 v19, v18
	s_nop 1
	v_permlane16_swap_b32_e32 v18, v19
	s_waitcnt lgkmcnt(0)
	v_max_f32_e32 v19, v19, v19
	v_max_f32_e32 v18, v18, v19
	v_mov_b32_e32 v19, v18
	s_nop 1
	v_permlane32_swap_b32_e32 v18, v19
	s_and_saveexec_b64 s[16:17], s[40:41]
	s_cbranch_execz .LBB7_1236
	s_waitcnt lgkmcnt(0)
	v_max_f32_e32 v19, v19, v19
	v_max_f32_e32 v18, v18, v18
	v_max_f32_e32 v18, v18, v19
	v_add_u32_e32 v19, s73, v159
	ds_write_b32 v19, v18 offset:2560
.LBB7_1236:
	s_or_b64 exec, exec, s[16:17]
	v_max_f32_e32 v18, v15, v15
	s_waitcnt lgkmcnt(0)
	v_max_f32_e32 v19, v14, v14
	v_max_f32_e32 v18, v19, v18
	v_max_f32_e32 v19, v11, v11
	v_max_f32_e32 v20, v10, v10
	v_max_f32_e32 v19, v20, v19
	v_max3_f32 v18, v16, v17, v18
	v_max3_f32 v19, v12, v13, v19
	v_max3_f32 v18, v18, s76, v19
	v_max_f32_e32 v19, v9, v9
	v_max_f32_e32 v20, v8, v8
	v_max_f32_e32 v19, v20, v19
	v_max_f32_e32 v20, v5, v5
	v_max_f32_e32 v21, v4, v4
	v_max_f32_e32 v20, v21, v20
	v_max3_f32 v19, v6, v7, v19
	v_max3_f32 v20, v2, v3, v20
	v_max3_f32 v18, v18, v19, v20
	v_mov_b32_e32 v19, v18
	s_nop 1
	v_permlane16_swap_b32_e32 v18, v19
	s_waitcnt lgkmcnt(0)
	v_max_f32_e32 v19, v19, v19
	v_max_f32_e32 v18, v18, v19
	v_mov_b32_e32 v19, v18
	s_nop 1
	v_permlane32_swap_b32_e32 v18, v19
	s_and_saveexec_b64 s[16:17], s[40:41]
	s_cbranch_execz .LBB7_1238
	s_waitcnt lgkmcnt(0)
	v_max_f32_e32 v19, v19, v19
	v_max_f32_e32 v18, v18, v18
	v_max_f32_e32 v18, v18, v19
	v_add_u32_e32 v19, s73, v159
	ds_write_b32 v19, v18 offset:2816
.LBB7_1238:
	s_or_b64 exec, exec, s[16:17]
	s_waitcnt lgkmcnt(0)
	s_barrier
	s_waitcnt lgkmcnt(0)
	ds_read_b128 v[18:21], v160
	s_waitcnt lgkmcnt(0)
	v_max_f32_e32 v21, v21, v21
	v_max_f32_e32 v20, v20, v20
	v_max_f32_e32 v20, v20, v21
	v_max3_f32 v18, v18, v19, v20
	v_sub_f32_e32 v19, v144, v18
	v_sub_f32_e32 v20, v145, v18
	v_exp_f32_e32 v144, v19
	v_exp_f32_e32 v145, v20
	v_sub_f32_e32 v19, v128, v18
	v_exp_f32_e32 v152, v19
	v_sub_f32_e32 v19, v129, v18
	v_exp_f32_e32 v153, v19
	v_sub_f32_e32 v20, v140, v18
	v_add_f32_e32 v19, 0, v144
	v_exp_f32_e32 v140, v20
	v_sub_f32_e32 v20, v141, v18
	v_add_f32_e32 v19, v145, v19
	v_exp_f32_e32 v141, v20
	v_sub_f32_e32 v20, v126, v18
	v_add_f32_e32 v19, v152, v19
	v_exp_f32_e32 v154, v20
	v_sub_f32_e32 v20, v127, v18
	v_add_f32_e32 v19, v153, v19
	v_exp_f32_e32 v155, v20
	v_sub_f32_e32 v20, v150, v18
	v_add_f32_e32 v19, v140, v19
	v_exp_f32_e32 v126, v20
	v_sub_f32_e32 v20, v151, v18
	v_add_f32_e32 v19, v141, v19
	v_exp_f32_e32 v127, v20
	v_sub_f32_e32 v20, v146, v18
	v_add_f32_e32 v19, v154, v19
	v_exp_f32_e32 v150, v20
	v_sub_f32_e32 v20, v147, v18
	v_add_f32_e32 v19, v155, v19
	v_exp_f32_e32 v151, v20
	v_sub_f32_e32 v20, v148, v18
	v_add_f32_e32 v19, v126, v19
	v_exp_f32_e32 v146, v20
	v_sub_f32_e32 v20, v149, v18
	v_add_f32_e32 v19, v127, v19
	v_exp_f32_e32 v147, v20
	v_sub_f32_e32 v20, v142, v18
	v_add_f32_e32 v19, v150, v19
	v_exp_f32_e32 v148, v20
	v_sub_f32_e32 v18, v143, v18
	v_add_f32_e32 v19, v151, v19
	v_exp_f32_e32 v149, v18
	v_add_f32_e32 v18, v146, v19
	v_add_f32_e32 v18, v147, v18
	v_add_f32_e32 v18, v148, v18
	v_add_f32_e32 v18, v149, v18
	v_mov_b32_e32 v19, v18
	s_nop 1
	v_permlane16_swap_b32_e32 v18, v19
	s_waitcnt lgkmcnt(0)
	v_add_f32_e32 v18, v18, v19
	v_mov_b32_e32 v19, v18
	s_nop 1
	v_permlane32_swap_b32_e32 v18, v19
	s_and_saveexec_b64 s[16:17], s[40:41]
	s_cbranch_execz .LBB7_1240
	s_waitcnt lgkmcnt(0)
	v_add_f32_e32 v18, v18, v19
	ds_write_b32 v161, v18
.LBB7_1240:
	s_or_b64 exec, exec, s[16:17]
	s_waitcnt lgkmcnt(0)
	ds_read_b128 v[18:21], v174
	s_waitcnt lgkmcnt(0)
	v_max_f32_e32 v21, v21, v21
	v_max_f32_e32 v20, v20, v20
	v_max_f32_e32 v20, v20, v21
	v_max3_f32 v18, v18, v19, v20
	v_sub_f32_e32 v19, v118, v18
	v_sub_f32_e32 v20, v119, v18
	v_exp_f32_e32 v118, v19
	v_sub_f32_e32 v21, v120, v18
	v_exp_f32_e32 v119, v20
	v_sub_f32_e32 v26, v121, v18
	v_exp_f32_e32 v128, v21
	v_exp_f32_e32 v129, v26
	v_sub_f32_e32 v20, v112, v18
	v_add_f32_e32 v19, 0, v118
	v_exp_f32_e32 v120, v20
	v_sub_f32_e32 v20, v113, v18
	v_add_f32_e32 v19, v119, v19
	v_exp_f32_e32 v121, v20
	v_sub_f32_e32 v20, v110, v18
	v_add_f32_e32 v19, v128, v19
	v_exp_f32_e32 v142, v20
	v_sub_f32_e32 v20, v111, v18
	v_add_f32_e32 v19, v129, v19
	v_exp_f32_e32 v143, v20
	v_sub_f32_e32 v20, v124, v18
	v_add_f32_e32 v19, v120, v19
	v_exp_f32_e32 v110, v20
	v_sub_f32_e32 v20, v125, v18
	v_add_f32_e32 v19, v121, v19
	v_exp_f32_e32 v111, v20
	v_sub_f32_e32 v20, v116, v18
	v_add_f32_e32 v19, v142, v19
	v_exp_f32_e32 v124, v20
	v_sub_f32_e32 v20, v117, v18
	v_add_f32_e32 v19, v143, v19
	v_exp_f32_e32 v125, v20
	v_sub_f32_e32 v20, v122, v18
	v_add_f32_e32 v19, v110, v19
	v_exp_f32_e32 v116, v20
	v_sub_f32_e32 v20, v123, v18
	v_add_f32_e32 v19, v111, v19
	v_exp_f32_e32 v117, v20
	v_sub_f32_e32 v20, v114, v18
	v_add_f32_e32 v19, v124, v19
	v_exp_f32_e32 v122, v20
	v_sub_f32_e32 v18, v115, v18
	v_add_f32_e32 v19, v125, v19
	v_exp_f32_e32 v123, v18
	v_add_f32_e32 v18, v116, v19
	v_add_f32_e32 v18, v117, v18
	v_add_f32_e32 v18, v122, v18
	v_add_f32_e32 v18, v123, v18
	v_mov_b32_e32 v19, v18
	s_nop 1
	v_permlane16_swap_b32_e32 v18, v19
	s_waitcnt lgkmcnt(0)
	v_add_f32_e32 v18, v18, v19
	v_mov_b32_e32 v19, v18
	s_nop 1
	v_permlane32_swap_b32_e32 v18, v19
	s_and_saveexec_b64 s[16:17], s[40:41]
	s_cbranch_execz .LBB7_1242
	s_waitcnt lgkmcnt(0)
	v_add_f32_e32 v18, v18, v19
	ds_write_b32 v161, v18 offset:256
.LBB7_1242:
	s_or_b64 exec, exec, s[16:17]
	s_waitcnt lgkmcnt(0)
	ds_read_b128 v[18:21], v175
	s_waitcnt lgkmcnt(0)
	v_max_f32_e32 v21, v21, v21
	v_max_f32_e32 v20, v20, v20
	v_max_f32_e32 v20, v20, v21
	v_max3_f32 v18, v18, v19, v20
	v_sub_f32_e32 v19, v104, v18
	v_sub_f32_e32 v20, v105, v18
	v_sub_f32_e32 v21, v102, v18
	v_exp_f32_e32 v102, v19
	v_sub_f32_e32 v26, v103, v18
	v_exp_f32_e32 v103, v20
	v_exp_f32_e32 v112, v21
	v_exp_f32_e32 v113, v26
	v_sub_f32_e32 v20, v96, v18
	v_add_f32_e32 v19, 0, v102
	v_exp_f32_e32 v104, v20
	v_sub_f32_e32 v20, v97, v18
	v_add_f32_e32 v19, v103, v19
	v_exp_f32_e32 v105, v20
	v_sub_f32_e32 v20, v94, v18
	v_add_f32_e32 v19, v112, v19
	v_exp_f32_e32 v114, v20
	v_sub_f32_e32 v20, v95, v18
	v_add_f32_e32 v19, v113, v19
	v_exp_f32_e32 v115, v20
	v_sub_f32_e32 v20, v108, v18
	v_add_f32_e32 v19, v104, v19
	v_exp_f32_e32 v94, v20
	v_sub_f32_e32 v20, v109, v18
	v_add_f32_e32 v19, v105, v19
	v_exp_f32_e32 v95, v20
	v_sub_f32_e32 v20, v100, v18
	v_add_f32_e32 v19, v114, v19
	v_exp_f32_e32 v108, v20
	v_sub_f32_e32 v20, v101, v18
	v_add_f32_e32 v19, v115, v19
	v_exp_f32_e32 v109, v20
	v_sub_f32_e32 v20, v106, v18
	v_add_f32_e32 v19, v94, v19
	v_exp_f32_e32 v100, v20
	v_sub_f32_e32 v20, v107, v18
	v_add_f32_e32 v19, v95, v19
	v_exp_f32_e32 v101, v20
	v_sub_f32_e32 v20, v98, v18
	v_add_f32_e32 v19, v108, v19
	v_exp_f32_e32 v106, v20
	v_sub_f32_e32 v18, v99, v18
	v_add_f32_e32 v19, v109, v19
	v_exp_f32_e32 v107, v18
	v_add_f32_e32 v18, v100, v19
	v_add_f32_e32 v18, v101, v18
	v_add_f32_e32 v18, v106, v18
	v_add_f32_e32 v18, v107, v18
	v_mov_b32_e32 v19, v18
	s_nop 1
	v_permlane16_swap_b32_e32 v18, v19
	s_waitcnt lgkmcnt(0)
	v_add_f32_e32 v18, v18, v19
	v_mov_b32_e32 v19, v18
	s_nop 1
	v_permlane32_swap_b32_e32 v18, v19
	s_and_saveexec_b64 s[16:17], s[40:41]
	s_cbranch_execz .LBB7_1244
	s_waitcnt lgkmcnt(0)
	v_add_f32_e32 v18, v18, v19
	ds_write_b32 v161, v18 offset:512
.LBB7_1244:
	s_or_b64 exec, exec, s[16:17]
	s_waitcnt lgkmcnt(0)
	ds_read_b128 v[18:21], v176
	s_waitcnt lgkmcnt(0)
	v_max_f32_e32 v21, v21, v21
	v_max_f32_e32 v20, v20, v20
	v_max_f32_e32 v20, v20, v21
	v_max3_f32 v18, v18, v19, v20
	v_sub_f32_e32 v19, v88, v18
	v_sub_f32_e32 v20, v89, v18
	v_sub_f32_e32 v21, v86, v18
	v_exp_f32_e32 v86, v19
	v_sub_f32_e32 v26, v87, v18
	v_exp_f32_e32 v87, v20
	v_exp_f32_e32 v96, v21
	v_exp_f32_e32 v97, v26
	v_sub_f32_e32 v20, v80, v18
	v_add_f32_e32 v19, 0, v86
	v_exp_f32_e32 v88, v20
	v_sub_f32_e32 v20, v81, v18
	v_add_f32_e32 v19, v87, v19
	v_exp_f32_e32 v89, v20
	v_sub_f32_e32 v20, v76, v18
	v_add_f32_e32 v19, v96, v19
	v_exp_f32_e32 v98, v20
	v_sub_f32_e32 v20, v77, v18
	v_add_f32_e32 v19, v97, v19
	v_exp_f32_e32 v99, v20
	v_sub_f32_e32 v20, v92, v18
	v_add_f32_e32 v19, v88, v19
	v_exp_f32_e32 v76, v20
	v_sub_f32_e32 v20, v93, v18
	v_add_f32_e32 v19, v89, v19
	v_exp_f32_e32 v77, v20
	v_sub_f32_e32 v20, v84, v18
	v_add_f32_e32 v19, v98, v19
	v_exp_f32_e32 v92, v20
	v_sub_f32_e32 v20, v85, v18
	v_add_f32_e32 v19, v99, v19
	v_exp_f32_e32 v93, v20
	v_sub_f32_e32 v20, v90, v18
	v_add_f32_e32 v19, v76, v19
	v_exp_f32_e32 v84, v20
	v_sub_f32_e32 v20, v91, v18
	v_add_f32_e32 v19, v77, v19
	v_exp_f32_e32 v85, v20
	v_sub_f32_e32 v20, v82, v18
	v_add_f32_e32 v19, v92, v19
	v_exp_f32_e32 v90, v20
	v_sub_f32_e32 v18, v83, v18
	v_add_f32_e32 v19, v93, v19
	v_exp_f32_e32 v91, v18
	v_add_f32_e32 v18, v84, v19
	v_add_f32_e32 v18, v85, v18
	v_add_f32_e32 v18, v90, v18
	v_add_f32_e32 v18, v91, v18
	v_mov_b32_e32 v19, v18
	s_nop 1
	v_permlane16_swap_b32_e32 v18, v19
	s_waitcnt lgkmcnt(0)
	v_add_f32_e32 v18, v18, v19
	v_mov_b32_e32 v19, v18
	s_nop 1
	v_permlane32_swap_b32_e32 v18, v19
	s_and_saveexec_b64 s[16:17], s[40:41]
	s_cbranch_execz .LBB7_1246
	s_waitcnt lgkmcnt(0)
	v_add_f32_e32 v18, v18, v19
	ds_write_b32 v161, v18 offset:768
.LBB7_1246:
	s_or_b64 exec, exec, s[16:17]
	s_waitcnt lgkmcnt(0)
	ds_read_b128 v[18:21], v177
	s_waitcnt lgkmcnt(0)
	v_max_f32_e32 v21, v21, v21
	v_max_f32_e32 v20, v20, v20
	v_max_f32_e32 v20, v20, v21
	v_max3_f32 v18, v18, v19, v20
	v_sub_f32_e32 v19, v72, v18
	v_sub_f32_e32 v20, v73, v18
	v_sub_f32_e32 v21, v66, v18
	v_exp_f32_e32 v66, v19
	v_sub_f32_e32 v26, v67, v18
	v_exp_f32_e32 v67, v20
	v_exp_f32_e32 v80, v21
	v_exp_f32_e32 v81, v26
	v_sub_f32_e32 v20, v64, v18
	v_add_f32_e32 v19, 0, v66
	v_exp_f32_e32 v72, v20
	v_sub_f32_e32 v20, v65, v18
	v_add_f32_e32 v19, v67, v19
	v_exp_f32_e32 v73, v20
	v_sub_f32_e32 v20, v62, v18
	v_add_f32_e32 v19, v80, v19
	v_exp_f32_e32 v82, v20
	v_sub_f32_e32 v20, v63, v18
	v_add_f32_e32 v19, v81, v19
	v_exp_f32_e32 v83, v20
	v_sub_f32_e32 v20, v78, v18
	v_add_f32_e32 v19, v72, v19
	v_exp_f32_e32 v42, v20
	v_sub_f32_e32 v20, v79, v18
	v_add_f32_e32 v19, v73, v19
	v_exp_f32_e32 v43, v20
	v_sub_f32_e32 v20, v70, v18
	v_add_f32_e32 v19, v82, v19
	v_exp_f32_e32 v64, v20
	v_sub_f32_e32 v20, v71, v18
	v_add_f32_e32 v19, v83, v19
	v_exp_f32_e32 v65, v20
	v_sub_f32_e32 v20, v74, v18
	v_add_f32_e32 v19, v42, v19
	v_exp_f32_e32 v62, v20
	v_sub_f32_e32 v20, v75, v18
	v_add_f32_e32 v19, v43, v19
	v_exp_f32_e32 v63, v20
	v_sub_f32_e32 v20, v68, v18
	v_add_f32_e32 v19, v64, v19
	v_exp_f32_e32 v70, v20
	v_sub_f32_e32 v18, v69, v18
	v_add_f32_e32 v19, v65, v19
	v_exp_f32_e32 v71, v18
	v_add_f32_e32 v18, v62, v19
	v_add_f32_e32 v18, v63, v18
	v_add_f32_e32 v18, v70, v18
	v_add_f32_e32 v18, v71, v18
	v_mov_b32_e32 v19, v18
	s_nop 1
	v_permlane16_swap_b32_e32 v18, v19
	s_waitcnt lgkmcnt(0)
	v_add_f32_e32 v18, v18, v19
	v_mov_b32_e32 v19, v18
	s_nop 1
	v_permlane32_swap_b32_e32 v18, v19
	s_and_saveexec_b64 s[16:17], s[40:41]
	s_cbranch_execz .LBB7_1248
	s_waitcnt lgkmcnt(0)
	v_add_f32_e32 v18, v18, v19
	ds_write_b32 v161, v18 offset:2048
.LBB7_1248:
	s_or_b64 exec, exec, s[16:17]
	s_waitcnt lgkmcnt(0)
	ds_read_b128 v[18:21], v178
	s_waitcnt lgkmcnt(0)
	v_max_f32_e32 v21, v21, v21
	v_max_f32_e32 v20, v20, v20
	v_max_f32_e32 v20, v20, v21
	v_max3_f32 v18, v18, v19, v20
	v_sub_f32_e32 v19, v54, v18
	v_sub_f32_e32 v20, v55, v18
	v_exp_f32_e32 v54, v19
	v_sub_f32_e32 v21, v56, v18
	v_exp_f32_e32 v55, v20
	v_sub_f32_e32 v26, v57, v18
	v_exp_f32_e32 v56, v21
	v_exp_f32_e32 v57, v26
	v_sub_f32_e32 v20, v48, v18
	v_add_f32_e32 v19, 0, v54
	v_exp_f32_e32 v48, v20
	v_sub_f32_e32 v20, v49, v18
	v_add_f32_e32 v19, v55, v19
	v_exp_f32_e32 v49, v20
	v_sub_f32_e32 v20, v46, v18
	v_add_f32_e32 v19, v56, v19
	v_exp_f32_e32 v68, v20
	v_sub_f32_e32 v20, v47, v18
	v_add_f32_e32 v19, v57, v19
	v_exp_f32_e32 v69, v20
	v_sub_f32_e32 v20, v60, v18
	v_add_f32_e32 v19, v48, v19
	v_exp_f32_e32 v20, v20
	v_sub_f32_e32 v21, v61, v18
	v_add_f32_e32 v19, v49, v19
	v_exp_f32_e32 v21, v21
	v_sub_f32_e32 v26, v52, v18
	v_add_f32_e32 v19, v68, v19
	v_exp_f32_e32 v46, v26
	v_sub_f32_e32 v26, v53, v18
	v_add_f32_e32 v19, v69, v19
	v_exp_f32_e32 v47, v26
	v_sub_f32_e32 v26, v58, v18
	v_add_f32_e32 v19, v20, v19
	v_exp_f32_e32 v44, v26
	v_sub_f32_e32 v26, v59, v18
	v_add_f32_e32 v19, v21, v19
	v_exp_f32_e32 v45, v26
	v_sub_f32_e32 v26, v50, v18
	v_add_f32_e32 v19, v46, v19
	v_exp_f32_e32 v50, v26
	v_sub_f32_e32 v18, v51, v18
	v_add_f32_e32 v19, v47, v19
	v_exp_f32_e32 v51, v18
	v_add_f32_e32 v18, v44, v19
	v_add_f32_e32 v18, v45, v18
	v_add_f32_e32 v18, v50, v18
	v_add_f32_e32 v18, v51, v18
	v_mov_b32_e32 v19, v18
	s_nop 1
	v_permlane16_swap_b32_e32 v18, v19
	s_waitcnt lgkmcnt(0)
	v_add_f32_e32 v18, v18, v19
	v_mov_b32_e32 v19, v18
	s_nop 1
	v_permlane32_swap_b32_e32 v18, v19
	s_and_saveexec_b64 s[16:17], s[40:41]
	s_cbranch_execz .LBB7_1250
	s_waitcnt lgkmcnt(0)
	v_add_f32_e32 v18, v18, v19
	ds_write_b32 v161, v18 offset:2304
.LBB7_1250:
	s_or_b64 exec, exec, s[16:17]
	ds_read_b128 v[26:29], v179
	s_waitcnt lgkmcnt(0)
	v_max_f32_e32 v18, v29, v29
	v_max_f32_e32 v19, v28, v28
	v_max_f32_e32 v18, v19, v18
	v_max3_f32 v52, v26, v27, v18
	v_sub_f32_e32 v18, v38, v52
	v_sub_f32_e32 v19, v39, v52
	v_exp_f32_e32 v26, v18
	v_sub_f32_e32 v28, v30, v52
	v_exp_f32_e32 v27, v19
	v_sub_f32_e32 v29, v31, v52
	v_exp_f32_e32 v30, v28
	v_exp_f32_e32 v31, v29
	v_sub_f32_e32 v19, v24, v52
	v_add_f32_e32 v18, 0, v26
	v_exp_f32_e32 v28, v19
	v_sub_f32_e32 v19, v25, v52
	v_add_f32_e32 v18, v27, v18
	v_exp_f32_e32 v29, v19
	v_sub_f32_e32 v19, v22, v52
	v_add_f32_e32 v18, v30, v18
	v_exp_f32_e32 v38, v19
	v_sub_f32_e32 v19, v23, v52
	v_add_f32_e32 v18, v31, v18
	v_exp_f32_e32 v39, v19
	v_add_f32_e32 v18, v28, v18
	v_add_f32_e32 v18, v29, v18
	v_add_f32_e32 v18, v38, v18
	v_add_f32_e32 v22, v39, v18
	v_sub_f32_e32 v18, v40, v52
	v_exp_f32_e32 v18, v18
	v_sub_f32_e32 v19, v41, v52
	v_exp_f32_e32 v19, v19
	v_sub_f32_e32 v23, v34, v52
	v_exp_f32_e32 v24, v23
	v_sub_f32_e32 v23, v35, v52
	v_exp_f32_e32 v25, v23
	v_add_f32_e32 v22, v18, v22
	v_add_f32_e32 v22, v19, v22
	v_add_f32_e32 v22, v24, v22
	v_add_f32_e32 v34, v25, v22
	v_sub_f32_e32 v22, v36, v52
	v_exp_f32_e32 v22, v22
	v_sub_f32_e32 v23, v37, v52
	v_exp_f32_e32 v23, v23
	v_sub_f32_e32 v32, v32, v52
	v_exp_f32_e32 v32, v32
	v_sub_f32_e32 v33, v33, v52
	v_exp_f32_e32 v33, v33
	v_add_f32_e32 v34, v22, v34
	v_add_f32_e32 v34, v23, v34
	v_add_f32_e32 v34, v32, v34
	v_add_f32_e32 v34, v33, v34
	v_mov_b32_e32 v35, v34
	s_nop 1
	v_permlane16_swap_b32_e32 v34, v35
	s_waitcnt lgkmcnt(0)
	v_add_f32_e32 v34, v34, v35
	v_mov_b32_e32 v35, v34
	s_nop 1
	v_permlane32_swap_b32_e32 v34, v35
	s_and_saveexec_b64 s[16:17], s[40:41]
	s_cbranch_execz .LBB7_1252
	s_waitcnt lgkmcnt(0)
	v_add_f32_e32 v34, v34, v35
	ds_write_b32 v161, v34 offset:2560
.LBB7_1252:
	s_or_b64 exec, exec, s[16:17]
	s_waitcnt lgkmcnt(0)
	ds_read_b128 v[34:37], v180
	s_waitcnt lgkmcnt(0)
	v_max_f32_e32 v37, v37, v37
	v_max_f32_e32 v36, v36, v36
	v_max_f32_e32 v36, v36, v37
	v_max3_f32 v34, v34, v35, v36
	v_sub_f32_e32 v16, v16, v34
	v_sub_f32_e32 v17, v17, v34
	v_sub_f32_e32 v35, v14, v34
	v_exp_f32_e32 v14, v16
	v_sub_f32_e32 v36, v15, v34
	v_exp_f32_e32 v15, v17
	v_exp_f32_e32 v16, v35
	v_exp_f32_e32 v17, v36
	v_sub_f32_e32 v12, v12, v34
	v_add_f32_e32 v35, 0, v14
	v_exp_f32_e32 v12, v12
	v_sub_f32_e32 v13, v13, v34
	v_add_f32_e32 v35, v15, v35
	v_exp_f32_e32 v13, v13
	v_sub_f32_e32 v10, v10, v34
	v_add_f32_e32 v35, v16, v35
	v_exp_f32_e32 v10, v10
	v_sub_f32_e32 v11, v11, v34
	v_add_f32_e32 v35, v17, v35
	v_exp_f32_e32 v11, v11
	v_sub_f32_e32 v6, v6, v34
	v_add_f32_e32 v35, v12, v35
	v_exp_f32_e32 v6, v6
	v_sub_f32_e32 v7, v7, v34
	v_add_f32_e32 v35, v13, v35
	v_exp_f32_e32 v7, v7
	v_sub_f32_e32 v8, v8, v34
	v_add_f32_e32 v35, v10, v35
	v_exp_f32_e32 v8, v8
	v_sub_f32_e32 v9, v9, v34
	v_add_f32_e32 v35, v11, v35
	v_exp_f32_e32 v9, v9
	v_sub_f32_e32 v2, v2, v34
	v_add_f32_e32 v35, v6, v35
	v_exp_f32_e32 v2, v2
	v_sub_f32_e32 v3, v3, v34
	v_add_f32_e32 v35, v7, v35
	v_exp_f32_e32 v3, v3
	v_sub_f32_e32 v4, v4, v34
	v_add_f32_e32 v35, v8, v35
	v_exp_f32_e32 v4, v4
	v_sub_f32_e32 v5, v5, v34
	v_add_f32_e32 v35, v9, v35
	v_exp_f32_e32 v5, v5
	v_add_f32_e32 v34, v2, v35
	v_add_f32_e32 v34, v3, v34
	v_add_f32_e32 v34, v4, v34
	v_add_f32_e32 v34, v5, v34
	v_mov_b32_e32 v35, v34
	s_nop 1
	v_permlane16_swap_b32_e32 v34, v35
	s_waitcnt lgkmcnt(0)
	v_add_f32_e32 v34, v34, v35
	v_mov_b32_e32 v35, v34
	s_nop 1
	v_permlane32_swap_b32_e32 v34, v35
	s_and_saveexec_b64 s[16:17], s[40:41]
	s_cbranch_execz .LBB7_1254
	s_waitcnt lgkmcnt(0)
	v_add_f32_e32 v34, v34, v35
	ds_write_b32 v161, v34 offset:2816
